# no grid barrier after attention: q-blocks published per row panel (write-through stores + counters), merge group starts when its 8 head units arrived; merged buffer moved to the dead ZA region
# speedup vs baseline: 1.0055x; 1.0055x over previous
.LBB0_91:
	s_andn2_b64 vcc, exec, s[2:3]
	s_cbranch_vccnz .LBB0_134
	s_lshl_b32 s7, s48, 10
	v_lshl_add_u32 v1, v0, 4, s7
	v_ashrrev_i32_e32 v2, 31, v1
	v_lshrrev_b32_e32 v2, 22, v2
	v_add_u32_e32 v2, v1, v2
	v_ashrrev_i32_e32 v2, 10, v2
	v_mul_i32_i24_e32 v3, 0x400, v2
	v_sub_u32_e32 v3, v1, v3
	v_lshrrev_b32_e32 v4, 4, v3
	v_bitop3_b32 v3, v4, v3, 32 bitop3:0x6c
	v_ashrrev_i32_e32 v5, 31, v3
	v_lshrrev_b32_e32 v5, 26, v5
	v_lshlrev_b32_e32 v4, 3, v2
	v_add_u32_e32 v5, v3, v5
	v_and_b32_e32 v4, -16, v4
	v_ashrrev_i32_e32 v6, 6, v5
	v_and_b32_e32 v5, 0xc0, v5
	v_add_u32_e32 v4, v6, v4
	v_sub_u32_e32 v3, v3, v5
	v_lshlrev_b32_e32 v2, 5, v2
	v_ashrrev_i16_sdwa v3, v202, sext(v3) dst_sel:DWORD dst_unused:UNUSED_PAD src0_sel:DWORD src1_sel:BYTE_0
	v_lshlrev_b32_e32 v5, 1, v4
	v_lshrrev_b32_e32 v7, 2, v4
	v_and_b32_e32 v6, 3, v6
	s_mov_b32 s2, 0x1fffe0
	v_and_b32_e32 v2, 32, v2
	v_bfe_i32 v3, v3, 0, 16
	v_and_b32_e32 v5, 24, v5
	v_and_b32_e32 v7, 4, v7
	v_and_or_b32 v6, v4, s2, v6
	v_or3_b32 v5, v6, v5, v7
	v_add_lshl_u32 v2, v2, v3, 1
	v_add_u32_e32 v1, 0x2000, v1
	v_lshl_add_u32 v130, v4, 11, v2
	v_lshl_add_u32 v131, v5, 11, v2
	v_ashrrev_i32_e32 v2, 31, v1
	v_lshrrev_b32_e32 v2, 22, v2
	v_add_u32_e32 v2, v1, v2
	v_ashrrev_i32_e32 v2, 10, v2
	v_mul_i32_i24_e32 v3, 0x400, v2
	v_sub_u32_e32 v1, v1, v3
	v_lshrrev_b32_e32 v3, 4, v1
	v_bitop3_b32 v1, v3, v1, 32 bitop3:0x6c
	v_ashrrev_i32_e32 v4, 31, v1
	v_lshrrev_b32_e32 v4, 26, v4
	v_add_u32_e32 v4, v1, v4
	v_ashrrev_i32_e32 v5, 6, v4
	v_and_b32_e32 v4, 0xffc0, v4
	v_lshlrev_b32_e32 v3, 3, v2
	v_sub_u32_e32 v1, v1, v4
	v_and_b32_e32 v3, -16, v3
	v_lshrrev_b16_e32 v4, 7, v1
	v_add_u32_e32 v3, v5, v3
	v_and_b32_e32 v4, 1, v4
	v_and_b32_e32 v5, 3, v5
	s_ashr_i32 s41, s40, 31
	s_ashr_i32 s81, s80, 31
	s_ashr_i32 s51, s48, 2
	v_add_u16_e32 v1, v1, v4
	v_and_or_b32 v5, v3, s2, v5
	s_lshl_b64 s[2:3], s[40:41], 19
	s_lshl_b64 s[10:11], s[80:81], 19
	v_lshlrev_b32_e32 v2, 5, v2
	v_ashrrev_i16_sdwa v1, v202, sext(v1) dst_sel:DWORD dst_unused:UNUSED_PAD src0_sel:DWORD src1_sel:BYTE_0
	v_lshlrev_b32_e32 v4, 1, v3
	v_lshrrev_b32_e32 v6, 2, v3
	s_add_u32 s6, s8, s10
	v_and_b32_e32 v2, 32, v2
	v_bfe_i32 v1, v1, 0, 16
	v_and_b32_e32 v4, 24, v4
	v_and_b32_e32 v6, 4, v6
	s_addc_u32 s11, s9, s11
	s_mov_b64 s[68:69], s[46:47]
	v_or3_b32 v4, v5, v4, v6
	v_add_lshl_u32 v1, v2, v1, 1
	s_add_u32 s46, s6, 0x1e80000
	v_lshl_add_u32 v132, v3, 11, v1
	v_lshl_add_u32 v133, v4, 11, v1
	s_addc_u32 s47, s11, 0
	s_add_i32 s10, s7, 0
	v_mov_b32_e32 v1, v131
	s_add_i32 m0, s10, 0x10000
	s_nop 0
	global_load_lds_dwordx4 v1, s[46:47]
	v_mov_b32_e32 v1, v133
	s_add_i32 m0, s10, 0x12000
	s_add_u32 s52, s6, 0x1ec0000
	global_load_lds_dwordx4 v1, s[46:47]
	s_addc_u32 s53, s11, 0
	s_add_i32 m0, s10, 0x14000
	v_mov_b32_e32 v1, v131
	s_nop 0
	global_load_lds_dwordx4 v1, s[52:53]
	s_add_i32 m0, s10, 0x16000
	v_mov_b32_e32 v1, v133
	s_add_u32 s6, s8, s2
	s_addc_u32 s11, s9, s3
	global_load_lds_dwordx4 v1, s[52:53]
	s_add_u32 s82, s6, 0x8500000
	v_mov_b32_e32 v1, v130
	s_addc_u32 s83, s11, 0
	s_mov_b32 m0, s10
	s_add_i32 s17, s10, 0x2000
	global_load_lds_dwordx4 v1, s[82:83]
	v_mov_b32_e32 v1, v132
	s_mov_b32 m0, s17
	s_add_u32 s52, s6, 0x8540000
	global_load_lds_dwordx4 v1, s[82:83]
	s_addc_u32 s53, s11, 0
	s_add_i32 s22, s10, 0x4000
	v_mov_b32_e32 v1, v130
	s_mov_b32 m0, s22
	s_add_i32 s41, s10, 0x6000
	global_load_lds_dwordx4 v1, s[52:53]
	v_mov_b32_e32 v1, v132
	s_mov_b32 m0, s41
	s_cmp_lg_u32 s51, 1
	global_load_lds_dwordx4 v1, s[52:53]
	s_cbranch_scc1 .LBB0_94
	s_barrier
.LBB0_94:
	v_mov_b32_e32 v64, v131
	s_waitcnt vmcnt(2)
	s_barrier
	s_add_i32 m0, s10, 0x18000
	v_lshl_add_u64 v[2:3], s[46:47], 0, v[64:65]
	v_lshl_add_u64 v[2:3], v[2:3], 0, s[24:25]
	v_mov_b32_e32 v64, v133
	global_load_lds_dwordx4 v[2:3], off
	s_add_i32 m0, s10, 0x1a000
	v_lshl_add_u64 v[2:3], s[46:47], 0, v[64:65]
	v_lshl_add_u64 v[2:3], v[2:3], 0, s[24:25]
	v_mov_b32_e32 v64, v130
	global_load_lds_dwordx4 v[2:3], off
	s_add_i32 s49, s10, 0x8000
	v_lshl_add_u64 v[2:3], s[82:83], 0, v[64:65]
	v_lshl_add_u64 v[2:3], v[2:3], 0, s[24:25]
	s_mov_b32 m0, s49
	v_mov_b32_e32 v64, v132
	global_load_lds_dwordx4 v[2:3], off
	s_add_i32 s50, s10, 0xa000
	v_lshl_add_u64 v[2:3], s[82:83], 0, v[64:65]
	s_and_b32 s6, s48, 3
	v_lshl_add_u64 v[2:3], v[2:3], 0, s[24:25]
	s_mov_b32 m0, s50
	s_add_u32 s52, s46, 0x40080
	global_load_lds_dwordx4 v[2:3], off
	v_mov_b32_e32 v2, v131
	s_addc_u32 s53, s47, 0
	s_add_i32 m0, s10, 0x1c000
	v_and_b32_e32 v1, 15, v0
	global_load_lds_dwordx4 v2, s[52:53]
	v_mov_b32_e32 v2, v133
	s_add_i32 m0, s10, 0x1e000
	s_lshl_b32 s11, s51, 6
	global_load_lds_dwordx4 v2, s[52:53]
	v_and_b32_e32 v2, 48, v0
	v_lshlrev_b32_e32 v0, 2, v0
	s_lshl_b32 s52, s6, 12
	s_lshl_b32 s51, s51, 13
	v_lshl_or_b32 v1, v1, 6, v2
	v_and_b32_e32 v0, 32, v0
	s_add_u32 s2, s4, s2
	s_waitcnt vmcnt(6)
	v_bitop3_b32 v134, v1, s52, v0 bitop3:0xde
	s_addc_u32 s3, s5, s3
	v_readlane_b32 s52, v254, 39
	v_bitop3_b32 v0, v1, s51, v0 bitop3:0xde
	v_readlane_b32 s53, v254, 40
	s_add_u32 s51, s52, s2
	v_mov_b32_e32 v8, 0
	s_addc_u32 s52, s53, s3
	s_mov_b32 s53, -2
	s_mov_b64 s[84:85], 0x8540080
	v_add_u32_e32 v135, 0, v0
	v_mov_b32_e32 v9, v8
	v_mov_b32_e32 v10, v8
	v_mov_b32_e32 v11, v8
	v_mov_b32_e32 v16, v8
	v_mov_b32_e32 v17, v8
	v_mov_b32_e32 v18, v8
	v_mov_b32_e32 v19, v8
	v_mov_b32_e32 v60, v8
	v_mov_b32_e32 v61, v8
	v_mov_b32_e32 v62, v8
	v_mov_b32_e32 v63, v8
	v_mov_b32_e32 v70, v8
	v_mov_b32_e32 v71, v8
	v_mov_b32_e32 v72, v8
	v_mov_b32_e32 v73, v8
	v_mov_b32_e32 v98, v8
	v_mov_b32_e32 v99, v8
	v_mov_b32_e32 v100, v8
	v_mov_b32_e32 v101, v8
	v_mov_b32_e32 v110, v8
	v_mov_b32_e32 v111, v8
	v_mov_b32_e32 v112, v8
	v_mov_b32_e32 v113, v8
	v_mov_b32_e32 v118, v8
	v_mov_b32_e32 v119, v8
	v_mov_b32_e32 v120, v8
	v_mov_b32_e32 v121, v8
	v_mov_b32_e32 v114, v8
	v_mov_b32_e32 v115, v8
	v_mov_b32_e32 v116, v8
	v_mov_b32_e32 v117, v8
	v_mov_b32_e32 v40, v8
	v_mov_b32_e32 v41, v8
	v_mov_b32_e32 v42, v8
	v_mov_b32_e32 v43, v8
	v_mov_b32_e32 v44, v8
	v_mov_b32_e32 v45, v8
	v_mov_b32_e32 v46, v8
	v_mov_b32_e32 v47, v8
	v_mov_b32_e32 v82, v8
	v_mov_b32_e32 v83, v8
	v_mov_b32_e32 v84, v8
	v_mov_b32_e32 v85, v8
	v_mov_b32_e32 v90, v8
	v_mov_b32_e32 v91, v8
	v_mov_b32_e32 v92, v8
	v_mov_b32_e32 v93, v8
	v_mov_b32_e32 v122, v8
	v_mov_b32_e32 v123, v8
	v_mov_b32_e32 v124, v8
	v_mov_b32_e32 v125, v8
	v_mov_b32_e32 v126, v8
	v_mov_b32_e32 v127, v8
	v_mov_b32_e32 v128, v8
	v_mov_b32_e32 v129, v8
	v_mov_b32_e32 v102, v8
	v_mov_b32_e32 v103, v8
	v_mov_b32_e32 v104, v8
	v_mov_b32_e32 v105, v8
	v_mov_b32_e32 v106, v8
	v_mov_b32_e32 v107, v8
	v_mov_b32_e32 v108, v8
	v_mov_b32_e32 v109, v8
	v_mov_b32_e32 v94, v8
	v_mov_b32_e32 v95, v8
	v_mov_b32_e32 v96, v8
	v_mov_b32_e32 v97, v8
	v_mov_b32_e32 v86, v8
	v_mov_b32_e32 v87, v8
	v_mov_b32_e32 v88, v8
	v_mov_b32_e32 v89, v8
	v_mov_b32_e32 v66, v8
	v_mov_b32_e32 v67, v8
	v_mov_b32_e32 v68, v8
	v_mov_b32_e32 v69, v8
	v_mov_b32_e32 v56, v8
	v_mov_b32_e32 v57, v8
	v_mov_b32_e32 v58, v8
	v_mov_b32_e32 v59, v8
	v_mov_b32_e32 v28, v8
	v_mov_b32_e32 v29, v8
	v_mov_b32_e32 v30, v8
	v_mov_b32_e32 v31, v8
	v_mov_b32_e32 v12, v8
	v_mov_b32_e32 v13, v8
	v_mov_b32_e32 v14, v8
	v_mov_b32_e32 v15, v8
	v_mov_b32_e32 v20, v8
	v_mov_b32_e32 v21, v8
	v_mov_b32_e32 v22, v8
	v_mov_b32_e32 v23, v8
	v_mov_b32_e32 v24, v8
	v_mov_b32_e32 v25, v8
	v_mov_b32_e32 v26, v8
	v_mov_b32_e32 v27, v8
	v_mov_b32_e32 v74, v8
	v_mov_b32_e32 v75, v8
	v_mov_b32_e32 v76, v8
	v_mov_b32_e32 v77, v8
	v_mov_b32_e32 v78, v8
	v_mov_b32_e32 v79, v8
	v_mov_b32_e32 v80, v8
	v_mov_b32_e32 v81, v8
	v_mov_b32_e32 v32, v8
	v_mov_b32_e32 v33, v8
	v_mov_b32_e32 v34, v8
	v_mov_b32_e32 v35, v8
	v_mov_b32_e32 v36, v8
	v_mov_b32_e32 v37, v8
	v_mov_b32_e32 v38, v8
	v_mov_b32_e32 v39, v8
	v_mov_b32_e32 v0, v8
	v_mov_b32_e32 v1, v8
	v_mov_b32_e32 v2, v8
	v_mov_b32_e32 v3, v8
	v_mov_b32_e32 v4, v8
	v_mov_b32_e32 v5, v8
	v_mov_b32_e32 v6, v8
	v_mov_b32_e32 v7, v8
	v_mov_b32_e32 v48, v8
	v_mov_b32_e32 v49, v8
	v_mov_b32_e32 v50, v8
	v_mov_b32_e32 v51, v8
	v_mov_b32_e32 v52, v8
	v_mov_b32_e32 v53, v8
	v_mov_b32_e32 v54, v8
	v_mov_b32_e32 v55, v8
	s_barrier
.LBB0_95:
	s_add_i32 s58, 0, 0x10000
	s_add_i32 s59, 0, 0x14000
	v_add_u32_e32 v64, s58, v134
	ds_read_b128 v[136:139], v64
	ds_read_b128 v[140:143], v64 offset:1024
	ds_read_b128 v[144:147], v64 offset:2048
	ds_read_b128 v[148:151], v64 offset:3072
	v_add_u32_e32 v64, s59, v134
	ds_read_b128 v[152:155], v64
	ds_read_b128 v[156:159], v64 offset:1024
	ds_read_b128 v[160:163], v64 offset:2048
	ds_read_b128 v[164:167], v64 offset:3072
	s_add_u32 s2, s84, 0xf7ac0080
	s_addc_u32 s3, s85, -1
	s_cmp_lg_u32 s53, 12
	s_cselect_b32 s54, s2, 0
	s_cselect_b32 s55, s3, 0
	s_add_u32 s2, s82, s54
	s_addc_u32 s3, s83, s55
	s_add_u32 s54, s46, s54
	s_addc_u32 s55, s47, s55
	s_add_i32 m0, s10, 0xc000
	v_mov_b32_e32 v64, v130
	s_add_u32 s56, s51, s84
	ds_read_b128 v[168:171], v135
	ds_read_b128 v[172:175], v135 offset:1024
	ds_read_b128 v[176:179], v135 offset:2048
	ds_read_b128 v[180:183], v135 offset:3072
	ds_read_b128 v[184:187], v135 offset:4096
	ds_read_b128 v[190:193], v135 offset:5120
	ds_read_b128 v[194:197], v135 offset:6144
	ds_read_b128 v[198:201], v135 offset:7168
	s_addc_u32 s57, s52, s85
	global_load_lds_dwordx4 v64, s[56:57]
	v_mov_b32_e32 v64, v132
	s_add_i32 m0, s10, 0xe000
	s_nop 0
	global_load_lds_dwordx4 v64, s[56:57]
	s_waitcnt vmcnt(8)
	s_waitcnt lgkmcnt(0)
	s_barrier
	s_setprio 1
	s_waitcnt lgkmcnt(0)
	v_mfma_f32_16x16x32_bf16 v[52:55], v[136:139], v[168:171], v[52:55]
	v_mfma_f32_16x16x32_bf16 v[48:51], v[144:147], v[168:171], v[48:51]
	v_mfma_f32_16x16x32_bf16 v[4:7], v[136:139], v[176:179], v[4:7]
	v_mfma_f32_16x16x32_bf16 v[0:3], v[144:147], v[176:179], v[0:3]
	v_mfma_f32_16x16x32_bf16 v[36:39], v[136:139], v[184:187], v[36:39]
	v_mfma_f32_16x16x32_bf16 v[32:35], v[144:147], v[184:187], v[32:35]
	v_mfma_f32_16x16x32_bf16 v[78:81], v[136:139], v[194:197], v[78:81]
	v_mfma_f32_16x16x32_bf16 v[74:77], v[144:147], v[194:197], v[74:77]
	v_mfma_f32_16x16x32_bf16 v[52:55], v[140:143], v[172:175], v[52:55]
	v_mfma_f32_16x16x32_bf16 v[48:51], v[148:151], v[172:175], v[48:51]
	v_mfma_f32_16x16x32_bf16 v[4:7], v[140:143], v[180:183], v[4:7]
	v_mfma_f32_16x16x32_bf16 v[0:3], v[148:151], v[180:183], v[0:3]
	v_mfma_f32_16x16x32_bf16 v[36:39], v[140:143], v[190:193], v[36:39]
	v_mfma_f32_16x16x32_bf16 v[32:35], v[148:151], v[190:193], v[32:35]
	v_mfma_f32_16x16x32_bf16 v[78:81], v[140:143], v[198:201], v[78:81]
	v_mfma_f32_16x16x32_bf16 v[74:77], v[148:151], v[198:201], v[74:77]
	s_setprio 0
	s_setprio 1
	v_mfma_f32_16x16x32_bf16 v[24:27], v[152:155], v[168:171], v[24:27]
	v_mfma_f32_16x16x32_bf16 v[20:23], v[160:163], v[168:171], v[20:23]
	v_mfma_f32_16x16x32_bf16 v[12:15], v[152:155], v[176:179], v[12:15]
	v_mfma_f32_16x16x32_bf16 v[28:31], v[160:163], v[176:179], v[28:31]
	v_mfma_f32_16x16x32_bf16 v[56:59], v[152:155], v[184:187], v[56:59]
	v_mfma_f32_16x16x32_bf16 v[66:69], v[160:163], v[184:187], v[66:69]
	v_mfma_f32_16x16x32_bf16 v[86:89], v[152:155], v[194:197], v[86:89]
	v_mfma_f32_16x16x32_bf16 v[94:97], v[160:163], v[194:197], v[94:97]
	v_mfma_f32_16x16x32_bf16 v[24:27], v[156:159], v[172:175], v[24:27]
	v_mfma_f32_16x16x32_bf16 v[20:23], v[164:167], v[172:175], v[20:23]
	v_mfma_f32_16x16x32_bf16 v[12:15], v[156:159], v[180:183], v[12:15]
	v_mfma_f32_16x16x32_bf16 v[28:31], v[164:167], v[180:183], v[28:31]
	v_mfma_f32_16x16x32_bf16 v[56:59], v[156:159], v[190:193], v[56:59]
	v_mfma_f32_16x16x32_bf16 v[66:69], v[164:167], v[190:193], v[66:69]
	v_mfma_f32_16x16x32_bf16 v[86:89], v[156:159], v[198:201], v[86:89]
	v_mfma_f32_16x16x32_bf16 v[94:97], v[164:167], v[198:201], v[94:97]
	s_setprio 0
	s_barrier
	v_mov_b32_e32 v64, v131
	s_add_i32 s56, s58, s7
	ds_read_b128 v[168:171], v135 offset:16384
	ds_read_b128 v[172:175], v135 offset:17408
	ds_read_b128 v[176:179], v135 offset:18432
	ds_read_b128 v[180:183], v135 offset:19456
	ds_read_b128 v[184:187], v135 offset:20480
	ds_read_b128 v[190:193], v135 offset:21504
	ds_read_b128 v[194:197], v135 offset:22528
	ds_read_b128 v[198:201], v135 offset:23552
	s_mov_b32 m0, s56
	s_nop 0
	global_load_lds_dwordx4 v64, s[54:55]
	v_mov_b32_e32 v64, v133
	s_add_i32 m0, s56, 0x2000
	s_add_u32 s56, s54, 0x40000
	global_load_lds_dwordx4 v64, s[54:55]
	s_addc_u32 s57, s55, 0
	v_mov_b32_e32 v64, v131
	s_add_i32 s58, s59, s7
	s_mov_b32 m0, s58
	s_nop 0
	global_load_lds_dwordx4 v64, s[56:57]
	v_mov_b32_e32 v64, v133
	s_add_i32 m0, s58, 0x2000
	s_nop 0
	global_load_lds_dwordx4 v64, s[56:57]
	v_mov_b32_e32 v64, v130
	s_mov_b32 m0, s10
	s_nop 0
	global_load_lds_dwordx4 v64, s[2:3]
	v_mov_b32_e32 v64, v132
	s_mov_b32 m0, s17
	s_nop 0
	global_load_lds_dwordx4 v64, s[2:3]
	s_waitcnt vmcnt(8)
	s_waitcnt lgkmcnt(0)
	s_barrier
	s_setprio 1
	s_waitcnt lgkmcnt(0)
	v_mfma_f32_16x16x32_bf16 v[106:109], v[136:139], v[168:171], v[106:109]
	v_mfma_f32_16x16x32_bf16 v[102:105], v[144:147], v[168:171], v[102:105]
	v_mfma_f32_16x16x32_bf16 v[126:129], v[136:139], v[176:179], v[126:129]
	v_mfma_f32_16x16x32_bf16 v[122:125], v[144:147], v[176:179], v[122:125]
	v_mfma_f32_16x16x32_bf16 v[90:93], v[136:139], v[184:187], v[90:93]
	v_mfma_f32_16x16x32_bf16 v[82:85], v[144:147], v[184:187], v[82:85]
	v_mfma_f32_16x16x32_bf16 v[44:47], v[136:139], v[194:197], v[44:47]
	v_mfma_f32_16x16x32_bf16 v[40:43], v[144:147], v[194:197], v[40:43]
	v_mfma_f32_16x16x32_bf16 v[106:109], v[140:143], v[172:175], v[106:109]
	v_mfma_f32_16x16x32_bf16 v[102:105], v[148:151], v[172:175], v[102:105]
	v_mfma_f32_16x16x32_bf16 v[126:129], v[140:143], v[180:183], v[126:129]
	v_mfma_f32_16x16x32_bf16 v[122:125], v[148:151], v[180:183], v[122:125]
	v_mfma_f32_16x16x32_bf16 v[90:93], v[140:143], v[190:193], v[90:93]
	v_mfma_f32_16x16x32_bf16 v[82:85], v[148:151], v[190:193], v[82:85]
	v_mfma_f32_16x16x32_bf16 v[44:47], v[140:143], v[198:201], v[44:47]
	v_mfma_f32_16x16x32_bf16 v[40:43], v[148:151], v[198:201], v[40:43]
	s_setprio 0
	s_setprio 1
	v_mfma_f32_16x16x32_bf16 v[114:117], v[152:155], v[168:171], v[114:117]
	v_mfma_f32_16x16x32_bf16 v[118:121], v[160:163], v[168:171], v[118:121]
	v_mfma_f32_16x16x32_bf16 v[110:113], v[152:155], v[176:179], v[110:113]
	v_mfma_f32_16x16x32_bf16 v[98:101], v[160:163], v[176:179], v[98:101]
	v_mfma_f32_16x16x32_bf16 v[70:73], v[152:155], v[184:187], v[70:73]
	v_mfma_f32_16x16x32_bf16 v[60:63], v[160:163], v[184:187], v[60:63]
	v_mfma_f32_16x16x32_bf16 v[16:19], v[152:155], v[194:197], v[16:19]
	v_mfma_f32_16x16x32_bf16 v[8:11], v[160:163], v[194:197], v[8:11]
	v_mfma_f32_16x16x32_bf16 v[114:117], v[156:159], v[172:175], v[114:117]
	v_mfma_f32_16x16x32_bf16 v[118:121], v[164:167], v[172:175], v[118:121]
	v_mfma_f32_16x16x32_bf16 v[110:113], v[156:159], v[180:183], v[110:113]
	v_mfma_f32_16x16x32_bf16 v[98:101], v[164:167], v[180:183], v[98:101]
	v_mfma_f32_16x16x32_bf16 v[70:73], v[156:159], v[190:193], v[70:73]
	v_mfma_f32_16x16x32_bf16 v[60:63], v[164:167], v[190:193], v[60:63]
	v_mfma_f32_16x16x32_bf16 v[16:19], v[156:159], v[198:201], v[16:19]
	v_mfma_f32_16x16x32_bf16 v[8:11], v[164:167], v[198:201], v[8:11]
	s_setprio 0
	s_barrier
	s_add_i32 s58, 0, 0x18000
	v_add_u32_e32 v64, s58, v134
	s_add_i32 s59, 0, 0x1c000
	ds_read_b128 v[136:139], v64
	ds_read_b128 v[140:143], v64 offset:1024
	ds_read_b128 v[144:147], v64 offset:2048
	ds_read_b128 v[148:151], v64 offset:3072
	v_add_u32_e32 v64, s59, v134
	ds_read_b128 v[152:155], v64
	ds_read_b128 v[156:159], v64 offset:1024
	ds_read_b128 v[160:163], v64 offset:2048
	ds_read_b128 v[164:167], v64 offset:3072
	s_add_u32 s56, s2, 0x40000
	v_mov_b32_e32 v64, v130
	s_mov_b32 m0, s22
	ds_read_b128 v[168:171], v135 offset:32768
	ds_read_b128 v[172:175], v135 offset:33792
	ds_read_b128 v[176:179], v135 offset:34816
	ds_read_b128 v[180:183], v135 offset:35840
	ds_read_b128 v[184:187], v135 offset:36864
	ds_read_b128 v[190:193], v135 offset:37888
	ds_read_b128 v[194:197], v135 offset:38912
	ds_read_b128 v[198:201], v135 offset:39936
	s_addc_u32 s57, s3, 0
	s_nop 0
	global_load_lds_dwordx4 v64, s[56:57]
	v_mov_b32_e32 v64, v132
	s_mov_b32 m0, s41
	s_nop 0
	global_load_lds_dwordx4 v64, s[56:57]
	s_waitcnt vmcnt(8)
	s_waitcnt lgkmcnt(0)
	s_barrier
	s_setprio 1
	s_waitcnt lgkmcnt(0)
	v_mfma_f32_16x16x32_bf16 v[52:55], v[136:139], v[168:171], v[52:55]
	v_mfma_f32_16x16x32_bf16 v[48:51], v[144:147], v[168:171], v[48:51]
	v_mfma_f32_16x16x32_bf16 v[4:7], v[136:139], v[176:179], v[4:7]
	v_mfma_f32_16x16x32_bf16 v[0:3], v[144:147], v[176:179], v[0:3]
	v_mfma_f32_16x16x32_bf16 v[36:39], v[136:139], v[184:187], v[36:39]
	v_mfma_f32_16x16x32_bf16 v[32:35], v[144:147], v[184:187], v[32:35]
	v_mfma_f32_16x16x32_bf16 v[78:81], v[136:139], v[194:197], v[78:81]
	v_mfma_f32_16x16x32_bf16 v[74:77], v[144:147], v[194:197], v[74:77]
	v_mfma_f32_16x16x32_bf16 v[52:55], v[140:143], v[172:175], v[52:55]
	v_mfma_f32_16x16x32_bf16 v[48:51], v[148:151], v[172:175], v[48:51]
	v_mfma_f32_16x16x32_bf16 v[4:7], v[140:143], v[180:183], v[4:7]
	v_mfma_f32_16x16x32_bf16 v[0:3], v[148:151], v[180:183], v[0:3]
	v_mfma_f32_16x16x32_bf16 v[36:39], v[140:143], v[190:193], v[36:39]
	v_mfma_f32_16x16x32_bf16 v[32:35], v[148:151], v[190:193], v[32:35]
	v_mfma_f32_16x16x32_bf16 v[78:81], v[140:143], v[198:201], v[78:81]
	v_mfma_f32_16x16x32_bf16 v[74:77], v[148:151], v[198:201], v[74:77]
	s_setprio 0
	s_setprio 1
	v_mfma_f32_16x16x32_bf16 v[24:27], v[152:155], v[168:171], v[24:27]
	v_mfma_f32_16x16x32_bf16 v[20:23], v[160:163], v[168:171], v[20:23]
	v_mfma_f32_16x16x32_bf16 v[12:15], v[152:155], v[176:179], v[12:15]
	v_mfma_f32_16x16x32_bf16 v[28:31], v[160:163], v[176:179], v[28:31]
	v_mfma_f32_16x16x32_bf16 v[56:59], v[152:155], v[184:187], v[56:59]
	v_mfma_f32_16x16x32_bf16 v[66:69], v[160:163], v[184:187], v[66:69]
	v_mfma_f32_16x16x32_bf16 v[86:89], v[152:155], v[194:197], v[86:89]
	v_mfma_f32_16x16x32_bf16 v[94:97], v[160:163], v[194:197], v[94:97]
	v_mfma_f32_16x16x32_bf16 v[24:27], v[156:159], v[172:175], v[24:27]
	v_mfma_f32_16x16x32_bf16 v[20:23], v[164:167], v[172:175], v[20:23]
	v_mfma_f32_16x16x32_bf16 v[12:15], v[156:159], v[180:183], v[12:15]
	v_mfma_f32_16x16x32_bf16 v[28:31], v[164:167], v[180:183], v[28:31]
	v_mfma_f32_16x16x32_bf16 v[56:59], v[156:159], v[190:193], v[56:59]
	v_mfma_f32_16x16x32_bf16 v[66:69], v[164:167], v[190:193], v[66:69]
	v_mfma_f32_16x16x32_bf16 v[86:89], v[156:159], v[198:201], v[86:89]
	v_mfma_f32_16x16x32_bf16 v[94:97], v[164:167], v[198:201], v[94:97]
	s_setprio 0
	s_barrier
	v_mov_b32_e32 v64, v131
	ds_read_b128 v[168:171], v135 offset:49152
	ds_read_b128 v[172:175], v135 offset:50176
	ds_read_b128 v[176:179], v135 offset:51200
	ds_read_b128 v[180:183], v135 offset:52224
	ds_read_b128 v[184:187], v135 offset:53248
	ds_read_b128 v[190:193], v135 offset:54272
	ds_read_b128 v[194:197], v135 offset:55296
	ds_read_b128 v[198:201], v135 offset:56320
	s_add_i32 s56, s58, s7
	v_lshl_add_u64 v[214:215], s[54:55], 0, v[64:65]
	v_lshl_add_u64 v[214:215], v[214:215], 0, s[24:25]
	s_mov_b32 m0, s56
	v_mov_b32_e32 v64, v133
	global_load_lds_dwordx4 v[214:215], off
	s_add_i32 m0, s56, 0x2000
	s_nop 0
	v_lshl_add_u64 v[214:215], s[54:55], 0, v[64:65]
	s_add_u32 s54, s54, 0x40080
	v_lshl_add_u64 v[214:215], v[214:215], 0, s[24:25]
	s_addc_u32 s55, s55, 0
	v_mov_b32_e32 v64, v131
	s_add_i32 s56, s59, s7
	global_load_lds_dwordx4 v[214:215], off
	s_mov_b32 m0, s56
	s_nop 0
	global_load_lds_dwordx4 v64, s[54:55]
	v_mov_b32_e32 v64, v133
	s_add_i32 m0, s56, 0x2000
	s_nop 0
	global_load_lds_dwordx4 v64, s[54:55]
	v_mov_b32_e32 v64, v130
	s_mov_b32 m0, s49
	v_lshl_add_u64 v[214:215], s[2:3], 0, v[64:65]
	v_lshl_add_u64 v[214:215], v[214:215], 0, s[24:25]
	v_mov_b32_e32 v64, v132
	global_load_lds_dwordx4 v[214:215], off
	s_mov_b32 m0, s50
	v_lshl_add_u64 v[214:215], s[2:3], 0, v[64:65]
	v_lshl_add_u64 v[214:215], v[214:215], 0, s[24:25]
	global_load_lds_dwordx4 v[214:215], off
	s_waitcnt vmcnt(8)
	s_waitcnt lgkmcnt(0)
	s_barrier
	s_setprio 1
	s_waitcnt lgkmcnt(0)
	v_mfma_f32_16x16x32_bf16 v[106:109], v[136:139], v[168:171], v[106:109]
	v_mfma_f32_16x16x32_bf16 v[102:105], v[144:147], v[168:171], v[102:105]
	v_mfma_f32_16x16x32_bf16 v[126:129], v[136:139], v[176:179], v[126:129]
	v_mfma_f32_16x16x32_bf16 v[122:125], v[144:147], v[176:179], v[122:125]
	v_mfma_f32_16x16x32_bf16 v[90:93], v[136:139], v[184:187], v[90:93]
	v_mfma_f32_16x16x32_bf16 v[82:85], v[144:147], v[184:187], v[82:85]
	v_mfma_f32_16x16x32_bf16 v[44:47], v[136:139], v[194:197], v[44:47]
	v_mfma_f32_16x16x32_bf16 v[40:43], v[144:147], v[194:197], v[40:43]
	v_mfma_f32_16x16x32_bf16 v[106:109], v[140:143], v[172:175], v[106:109]
	v_mfma_f32_16x16x32_bf16 v[102:105], v[148:151], v[172:175], v[102:105]
	v_mfma_f32_16x16x32_bf16 v[126:129], v[140:143], v[180:183], v[126:129]
	v_mfma_f32_16x16x32_bf16 v[122:125], v[148:151], v[180:183], v[122:125]
	v_mfma_f32_16x16x32_bf16 v[90:93], v[140:143], v[190:193], v[90:93]
	v_mfma_f32_16x16x32_bf16 v[82:85], v[148:151], v[190:193], v[82:85]
	v_mfma_f32_16x16x32_bf16 v[44:47], v[140:143], v[198:201], v[44:47]
	v_mfma_f32_16x16x32_bf16 v[40:43], v[148:151], v[198:201], v[40:43]
	s_setprio 0
	s_setprio 1
	v_mfma_f32_16x16x32_bf16 v[114:117], v[152:155], v[168:171], v[114:117]
	v_mfma_f32_16x16x32_bf16 v[118:121], v[160:163], v[168:171], v[118:121]
	v_mfma_f32_16x16x32_bf16 v[110:113], v[152:155], v[176:179], v[110:113]
	v_mfma_f32_16x16x32_bf16 v[98:101], v[160:163], v[176:179], v[98:101]
	v_mfma_f32_16x16x32_bf16 v[70:73], v[152:155], v[184:187], v[70:73]
	v_mfma_f32_16x16x32_bf16 v[60:63], v[160:163], v[184:187], v[60:63]
	v_mfma_f32_16x16x32_bf16 v[16:19], v[152:155], v[194:197], v[16:19]
	v_mfma_f32_16x16x32_bf16 v[8:11], v[160:163], v[194:197], v[8:11]
	v_mfma_f32_16x16x32_bf16 v[114:117], v[156:159], v[172:175], v[114:117]
	v_mfma_f32_16x16x32_bf16 v[118:121], v[164:167], v[172:175], v[118:121]
	v_mfma_f32_16x16x32_bf16 v[110:113], v[156:159], v[180:183], v[110:113]
	v_mfma_f32_16x16x32_bf16 v[98:101], v[164:167], v[180:183], v[98:101]
	v_mfma_f32_16x16x32_bf16 v[70:73], v[156:159], v[190:193], v[70:73]
	v_mfma_f32_16x16x32_bf16 v[60:63], v[164:167], v[190:193], v[60:63]
	v_mfma_f32_16x16x32_bf16 v[16:19], v[156:159], v[198:201], v[16:19]
	v_mfma_f32_16x16x32_bf16 v[8:11], v[164:167], v[198:201], v[8:11]
	s_setprio 0
	s_barrier
	s_add_i32 s53, s53, 2
	s_add_u32 s84, s84, 0x100
	s_addc_u32 s85, s85, 0
	s_cmp_gt_u32 s53, 13
	s_cbranch_scc0 .LBB0_95
	s_cmp_lt_u32 s48, 4
	s_cbranch_scc0 .LBB0_98
	s_barrier

.LBB0_139:
	s_add_u32 s40, s8, 0x2500000
	s_addc_u32 s41, s9, 0
	s_add_u32 s46, s8, 0x4500000
	s_addc_u32 s47, s9, 0
	v_mov_b32_e32 v64, v193
	s_add_u32 s56, s8, 0x8500000
	s_waitcnt vmcnt(2)
	s_barrier
	s_addc_u32 s57, s9, 0
	v_lshl_add_u64 v[2:3], s[54:55], 0, v[64:65]
	s_add_i32 m0, s50, 0x18000
	v_lshl_add_u64 v[2:3], v[2:3], 0, s[24:25]
	v_mov_b32_e32 v64, v195
	global_load_lds_dwordx4 v[2:3], off
	s_add_i32 m0, s50, 0x1a000
	v_lshl_add_u64 v[2:3], s[54:55], 0, v[64:65]
	v_lshl_add_u64 v[2:3], v[2:3], 0, s[24:25]
	v_mov_b32_e32 v64, v192
	s_sext_i32_i8 s3, s22
	global_load_lds_dwordx4 v[2:3], off
	s_add_i32 s22, s50, 0x8000
	v_lshl_add_u64 v[2:3], s[92:93], 0, v[64:65]
	v_lshl_add_u64 v[2:3], v[2:3], 0, s[24:25]
	s_mov_b32 m0, s22
	v_mov_b32_e32 v64, v194
	global_load_lds_dwordx4 v[2:3], off
	s_add_i32 s58, s50, 0xa000
	v_lshl_add_u64 v[2:3], s[92:93], 0, v[64:65]
	v_lshl_add_u64 v[2:3], v[2:3], 0, s[24:25]
	s_mov_b32 m0, s58
	s_add_u32 s62, s54, 0x20080
	v_mov_b32_e32 v1, v193
	global_load_lds_dwordx4 v[2:3], off
	s_addc_u32 s63, s55, 0
	s_add_i32 m0, s50, 0x1c000
	v_lshlrev_b32_e32 v2, 6, v0
	global_load_lds_dwordx4 v1, s[62:63]
	v_mov_b32_e32 v1, v195
	s_add_i32 m0, s50, 0x1e000
	s_movk_i32 s61, 0x3c0
	global_load_lds_dwordx4 v1, s[62:63]
	v_and_b32_e32 v1, 48, v0
	v_lshlrev_b32_e32 v0, 2, v0
	s_lshl_b32 s59, s60, 6
	s_lshl_b32 s60, s60, 13
	v_and_or_b32 v1, v2, s61, v1
	v_and_b32_e32 v0, 32, v0
	v_bitop3_b32 v2, v1, s60, v0 bitop3:0xde
	s_lshl_b32 s60, s48, 5
	s_and_b32 s62, s60, 0x60
	s_waitcnt vmcnt(6)
	s_lshl_b32 s60, s62, 7
	s_cmp_lt_u32 s48, 4
	v_bitop3_b32 v196, v1, s60, v0 bitop3:0xde
	s_mov_b32 s63, 0
	s_cselect_b64 s[80:81], -1, 0
	v_add_u32_e32 v197, 0, v2
	s_barrier
	s_branch .LBB0_142

.LBB0_160:
	ds_bpermute_b32 v34, v161, v96
	v_lshlrev_b64 v[32:33], 11, v[146:147]
	v_lshl_add_u64 v[32:33], s[8:9], 0, v[32:33]
	v_lshl_add_u64 v[32:33], v[32:33], 0, s[22:23]
	v_lshl_add_u64 v[32:33], v[32:33], 0, v[64:65]
	s_waitcnt lgkmcnt(0)
	v_add_f32_e32 v34, v96, v34
	v_div_scale_f32 v35, s[0:1], v34, v34, 1.0
	v_rcp_f32_e32 v36, v35
	v_div_scale_f32 v37, vcc, 1.0, v34, 1.0
	s_mov_b64 s[0:1], 0x6500400
	v_fma_f32 v38, -v35, v36, 1.0
	v_fmac_f32_e32 v36, v38, v36
	v_mul_f32_e32 v38, v37, v36
	v_fma_f32 v39, -v35, v38, v37
	v_fmac_f32_e32 v38, v39, v36
	v_fma_f32 v35, -v35, v38, v37
	v_div_fmas_f32 v35, v35, v36, v38
	v_div_fixup_f32 v34, v35, v34, 1.0
	v_lshl_add_u64 v[36:37], v[32:33], 0, s[0:1]
	v_pk_mul_f32 v[0:1], v[0:1], v[34:35] op_sel_hi:[1,0]
	v_pk_mul_f32 v[2:3], v[2:3], v[34:35] op_sel_hi:[1,0]
	s_mov_b32 s0, 0x6500000
	v_cvt_pk_bf16_f32 v0, v0, v1
	v_cvt_pk_bf16_f32 v1, v2, v3
	v_add_co_u32_e32 v2, vcc, s0, v32
	s_mov_b64 s[0:1], 0
	s_nop 0
	v_addc_co_u32_e32 v3, vcc, 0, v33, vcc
	global_store_dwordx2 v[2:3], v[0:1], off offset:1024 sc1
	v_pk_mul_f32 v[0:1], v[16:17], v[34:35] op_sel_hi:[1,0]
	v_pk_mul_f32 v[2:3], v[18:19], v[34:35] op_sel_hi:[1,0]
	v_cvt_pk_bf16_f32 v0, v0, v1
	v_cvt_pk_bf16_f32 v1, v2, v3
	global_store_dwordx2 v[36:37], v[0:1], off offset:64 sc1
	v_pk_mul_f32 v[0:1], v[4:5], v[34:35] op_sel_hi:[1,0]
	v_pk_mul_f32 v[2:3], v[6:7], v[34:35] op_sel_hi:[1,0]
	v_cvt_pk_bf16_f32 v0, v0, v1
	v_cvt_pk_bf16_f32 v1, v2, v3
	global_store_dwordx2 v[36:37], v[0:1], off offset:16 sc1
	v_pk_mul_f32 v[0:1], v[20:21], v[34:35] op_sel_hi:[1,0]
	v_pk_mul_f32 v[2:3], v[22:23], v[34:35] op_sel_hi:[1,0]
	v_cvt_pk_bf16_f32 v0, v0, v1
	v_cvt_pk_bf16_f32 v1, v2, v3
	global_store_dwordx2 v[36:37], v[0:1], off offset:80 sc1
	v_pk_mul_f32 v[0:1], v[8:9], v[34:35] op_sel_hi:[1,0]
	v_pk_mul_f32 v[2:3], v[10:11], v[34:35] op_sel_hi:[1,0]
	v_cvt_pk_bf16_f32 v0, v0, v1
	v_cvt_pk_bf16_f32 v1, v2, v3
	global_store_dwordx2 v[36:37], v[0:1], off offset:32 sc1
	v_pk_mul_f32 v[0:1], v[24:25], v[34:35] op_sel_hi:[1,0]
	v_pk_mul_f32 v[2:3], v[26:27], v[34:35] op_sel_hi:[1,0]
	v_cvt_pk_bf16_f32 v0, v0, v1
	v_cvt_pk_bf16_f32 v1, v2, v3
	global_store_dwordx2 v[36:37], v[0:1], off offset:96 sc1
	v_pk_mul_f32 v[0:1], v[12:13], v[34:35] op_sel_hi:[1,0]
	v_pk_mul_f32 v[2:3], v[14:15], v[34:35] op_sel_hi:[1,0]
	v_cvt_pk_bf16_f32 v0, v0, v1
	v_cvt_pk_bf16_f32 v1, v2, v3
	global_store_dwordx2 v[36:37], v[0:1], off offset:48 sc1
	v_pk_mul_f32 v[0:1], v[28:29], v[34:35] op_sel_hi:[1,0]
	v_pk_mul_f32 v[2:3], v[30:31], v[34:35] op_sel_hi:[1,0]
	v_cvt_pk_bf16_f32 v0, v0, v1
	v_cvt_pk_bf16_f32 v1, v2, v3
	s_and_b64 vcc, exec, s[40:41]
	global_store_dwordx2 v[36:37], v[0:1], off offset:112 sc1
	s_cbranch_vccnz .LBB0_158
.LBB0_161:
	s_and_b64 s[2:3], s[0:1], exec
	s_cselect_b32 s2, s62, s59
	s_add_i32 s65, s2, s11
	v_or_b32_e32 v216, s65, v101
	v_add_u32_e32 v146, s58, v216
	v_mad_i64_i32 v[0:1], s[40:41], v146, s33, v[114:115]
	global_load_dwordx4 v[66:69], v[0:1], off
	global_load_dwordx4 v[70:73], v[0:1], off offset:32
	global_load_dwordx4 v[74:77], v[0:1], off offset:64
	global_load_dwordx4 v[78:81], v[0:1], off offset:96
	global_load_dwordx4 v[82:85], v[0:1], off offset:128
	global_load_dwordx4 v[86:89], v[0:1], off offset:160
	v_add_u32_e32 v0, s17, v154
	v_add_u32_e32 v1, 0x400, v0
	v_readfirstlane_b32 s40, v0
	s_mov_b32 m0, s40
	v_readfirstlane_b32 s40, v1
	v_add_u32_e32 v1, s46, v154
	v_add_u32_e32 v2, 0x4000, v1
	s_waitcnt vmcnt(0)
	s_barrier
	s_cmp_eq_u64 s[0:1], 0
	s_cbranch_scc0 .Las_skip
	s_cmp_eq_u32 s48, 0
	s_cbranch_scc0 .Las_skip
	v_readlane_b32 s98, v253, 55
	s_bfe_u32 s99, s98, 0x30003
	s_sub_i32 s99, 15, s99
	s_bfe_u32 s98, s98, 0x20001
	s_lshl_b32 s98, s98, 4
	s_add_i32 s98, s98, s99
	s_lshl_b32 s98, s98, 8
	s_add_i32 s98, s98, 0x4058
	s_cmp_eq_u32 s14, 16
	s_cselect_b32 s99, 4, 0
	s_add_i32 s98, s98, s99
	v_mov_b32_e32 v244, s98
	s_add_i32 s99, s99, 0x4060
	v_mov_b32_e32 v245, s99
	v_cmp_eq_u32_e32 vcc, 0, v203
	s_and_saveexec_b64 s[98:99], vcc
	global_atomic_add v244, v202, s[12:13]
	global_atomic_add v245, v202, s[12:13]
	s_mov_b64 exec, s[98:99]
.Las_skip:
	global_load_lds_dwordx4 v[124:125], off
	s_mov_b32 m0, s40
	v_readfirstlane_b32 s40, v2
	v_add_u32_e32 v2, 0x6000, v0
	global_load_lds_dwordx4 v[126:127], off
	s_mov_b32 m0, s40
	v_readfirstlane_b32 s40, v2
	v_add_u32_e32 v2, 0x6400, v0
	global_load_lds_dwordx4 v[116:117], off
	s_mov_b32 m0, s40
	v_readfirstlane_b32 s40, v2
	v_add_u32_e32 v1, 0xa000, v1
	global_load_lds_dwordx4 v[128:129], off
	s_mov_b32 m0, s40
	v_readfirstlane_b32 s40, v1
	v_add_u32_e32 v1, 0xc000, v0
	global_load_lds_dwordx4 v[130:131], off
	s_mov_b32 m0, s40
	v_readfirstlane_b32 s40, v1
	v_add_u32_e32 v0, 0xc400, v0
	global_load_lds_dwordx4 v[118:119], off
	s_mov_b32 m0, s40
	v_readfirstlane_b32 s40, v0
	v_add_u32_e32 v0, s47, v154
	global_load_lds_dwordx4 v[132:133], off
	s_mov_b32 m0, s40
	v_readfirstlane_b32 s40, v0
	v_add_u32_e32 v0, s49, v154
	global_load_lds_dwordx4 v[134:135], off
	s_mov_b32 m0, s40
	v_readfirstlane_b32 s40, v0
	v_add_u32_e32 v0, 0x400, v0
	global_load_lds_dwordx4 v[120:121], off
	s_mov_b32 m0, s40
	v_readfirstlane_b32 s40, v0
	v_add_u32_e32 v0, s50, v154
	global_load_lds_dwordx4 v[136:137], off
	s_mov_b32 m0, s40
	v_readfirstlane_b32 s40, v0
	global_load_lds_dwordx4 v[138:139], off
	s_mov_b32 m0, s40
	v_add_u32_e32 v0, v155, v156
	global_load_lds_dwordx4 v[122:123], off
	s_waitcnt vmcnt(0)
	s_barrier
	ds_read_b128 v[0:3], v0
	s_add_i32 s3, s2, 0x100
	s_lshr_b32 s63, s3, 6
	s_lshr_b32 s64, s3, 7
	s_waitcnt vmcnt(0) lgkmcnt(0)
	v_mfma_f32_32x32x16_bf16 v[32:47], v[0:3], v[66:69], 0
	v_add_u32_e32 v0, v155, v157
	ds_read_b128 v[0:3], v0
	s_mov_b32 s80, 0
	s_cmp_eq_u32 s2, 0
	s_waitcnt lgkmcnt(0)
	v_mfma_f32_32x32x16_bf16 v[32:47], v[0:3], v[70:73], v[32:47]
	v_add_u32_e32 v0, v155, v158
	ds_read_b128 v[0:3], v0
	s_waitcnt lgkmcnt(0)
	v_mfma_f32_32x32x16_bf16 v[32:47], v[0:3], v[74:77], v[32:47]
	v_add_u32_e32 v0, v155, v159
	ds_read_b128 v[0:3], v0
	s_waitcnt lgkmcnt(0)
	v_mfma_f32_32x32x16_bf16 v[32:47], v[0:3], v[78:81], v[32:47]
	v_add_u32_e32 v0, v155, v160
	ds_read_b128 v[0:3], v0
	s_waitcnt lgkmcnt(0)
	v_mfma_f32_32x32x16_bf16 v[32:47], v[0:3], v[82:85], v[32:47]
	v_add_u32_e32 v0, v155, v162
	ds_read_b128 v[0:3], v0
	s_waitcnt lgkmcnt(0)
	v_mfma_f32_32x32x16_bf16 v[32:47], v[0:3], v[86:89], v[32:47]
	s_cbranch_scc1 .LBB0_180
	s_max_u32 s2, s64, 3
	v_mov_b32_e32 v14, v65
	v_mov_b32_e32 v15, v65
	s_mul_i32 s40, s2, 0xc000
	v_mov_b32_e32 v0, v65
	v_mov_b32_e32 v1, v65
	v_mov_b32_e32 v2, v65
	v_mov_b32_e32 v3, v65
	v_mov_b32_e32 v4, v65
	v_mov_b32_e32 v5, v65
	v_mov_b32_e32 v6, v65
	v_mov_b32_e32 v7, v65
	v_mov_b32_e32 v8, v65
	v_mov_b32_e32 v9, v65
	v_mov_b32_e32 v10, v65
	v_mov_b32_e32 v11, v65
	v_mov_b32_e32 v12, v65
	v_mov_b32_e32 v13, v65
	v_mov_b64_e32 v[30:31], v[14:15]
	s_add_i32 s80, s2, -2
	s_add_i32 s40, s40, 0xfffe8000
	s_mov_b32 s41, 0
	v_mov_b32_e32 v217, 0xf149f2ca
	v_mov_b32_e32 v96, 0
	s_mov_b32 s66, 2
	s_mov_b32 s67, 4
	s_mov_b32 s68, 5
	v_mov_b64_e32 v[148:149], v[144:145]
	v_mov_b64_e32 v[150:151], v[142:143]
	v_mov_b64_e32 v[152:153], v[140:141]
	s_mov_b32 s69, 0
	v_mov_b64_e32 v[28:29], v[12:13]
	v_mov_b64_e32 v[26:27], v[10:11]
	v_mov_b64_e32 v[24:25], v[8:9]
	v_mov_b64_e32 v[22:23], v[6:7]
	v_mov_b64_e32 v[20:21], v[4:5]
	v_mov_b64_e32 v[18:19], v[2:3]
	v_mov_b64_e32 v[16:17], v[0:1]
	s_branch .Lam_entry

.Lrp_done:
	s_cmp_eq_u32 s14, 11
	s_cbranch_scc1 .LBB0_681
	s_cmp_ge_i32 s17, s15
	s_cbranch_scc1 .LBB0_681
	v_readlane_b32 s99, v255, 59
	s_lshr_b32 s98, 0x1705c0, s14
	s_and_b32 s98, s98, s99
	s_bitcmp1_b32 s98, 0
	s_cbranch_scc0 .Lgg_no
	s_waitcnt vmcnt(0)
	s_barrier
	s_and_saveexec_b64 s[2:3], s[86:87]
	s_cbranch_execz .Lgg_join
	v_readlane_b32 s6, v253, 55
	s_and_b32 s7, s6, 7
	s_lshl_b32 s7, s7, 3
	s_bfe_u32 s6, s6, 0x30003
	s_add_i32 s6, s6, s7
	s_cmp_eq_u32 s14, 16
	s_cselect_b32 s10, 4, 0
	s_cmp_eq_u32 s14, 17
	s_cselect_b32 s10, 4, s10
	s_cmp_eq_u32 s14, 6
	s_cselect_b32 s11, 1, 0
	s_cmp_eq_u32 s14, 16
	s_cselect_b32 s11, 1, s11
	s_cmp_eq_u32 s11, 1
	s_cbranch_scc0 .Lgg_std
	v_readlane_b32 s7, v253, 55
	s_bfe_u32 s8, s7, 0x30003
	s_bfe_u32 s7, s7, 0x20001
	s_lshl_b32 s7, s7, 4
	s_add_i32 s7, s7, s8
	s_lshl_b32 s7, s7, 8
	s_add_i32 s7, s7, 0x4058
	s_add_i32 s7, s7, s10
	v_mov_b32_e32 v20, s7
	s_add_i32 s9, s10, 0x4060
	v_mov_b32_e32 v21, s9
	global_atomic_add v20, v202, s[12:13]
	global_atomic_add v21, v202, s[12:13]
	s_lshl_b32 s7, s6, 8
	s_add_i32 s7, s7, 0x4058
	s_add_i32 s7, s7, s10
	v_mov_b32_e32 v20, s7
	s_mov_b32 s58, 0
.Lgg_aspin:
	global_load_dword v22, v20, s[12:13] sc1
	s_waitcnt vmcnt(0)
	v_cmp_gt_u32_e32 vcc, 8, v22
	s_cbranch_vccz .Lgg_done
	s_sleep 1
	s_add_i32 s58, s58, 1
	s_cmp_lt_u32 s58, 0x40001
	s_cbranch_scc1 .Lgg_aspin
	s_branch .Lgg_done
.Lgg_std:
	s_lshl_b32 s7, s6, 8
	s_add_i32 s7, s7, 0x4040
	s_cmp_eq_u32 s14, 18
	s_cselect_b32 s8, 4, 0
	s_cmp_eq_u32 s14, 20
	s_cselect_b32 s8, 8, s8
	s_cmp_eq_u32 s14, 7
	s_cselect_b32 s8, 12, s8
	s_cmp_eq_u32 s14, 17
	s_cselect_b32 s8, 16, s8
	s_cmp_eq_u32 s14, 10
	s_cselect_b32 s8, 20, s8
	s_add_i32 s8, s7, s8
	v_mov_b32_e32 v20, s8
	s_mov_b32 s9, s8
	s_mov_b32 s11, 0
	v_mov_b32_e32 v30, 4
	s_cmp_eq_u32 s14, 7
	s_cselect_b32 s7, 1, 0
	s_cmp_eq_u32 s14, 17
	s_cselect_b32 s7, 1, s7
	s_cmp_eq_u32 s7, 1
	s_cbranch_scc0 .Lgg_d0
	s_add_i32 s9, s10, 0x4060
	v_mov_b32_e32 v30, 0x200
.Lgg_d0:
	s_cmp_eq_u32 s14, 8
	s_cselect_b32 s7, 1, 0
	s_cmp_eq_u32 s14, 18
	s_cselect_b32 s7, 1, s7
	s_cmp_eq_u32 s7, 1
	s_cbranch_scc0 .Lgg_d1
	s_lshl_b32 s9, s6, 2
	s_and_b32 s9, s9, 63
	s_lshl_b32 s9, s9, 8
	s_add_i32 s9, s9, 0x4040
	s_cmp_lt_u32 s6, 48
	s_cselect_b32 s7, 12, 0
	s_add_i32 s9, s9, s7
	s_cmp_eq_u32 s14, 18
	s_cselect_b32 s7, 4, 0
	s_add_i32 s9, s9, s7
	s_movk_i32 s11, 0x100
.Lgg_d1:
	s_cmp_eq_u32 s14, 10
	s_cbranch_scc0 .Lgg_d2
	s_cmp_lt_u32 s6, 22
	s_cbranch_scc0 .Lgg_d2
	s_add_i32 s9, s6, 42
	s_lshl_b32 s9, s9, 8
	s_add_i32 s9, s9, 0x4054
.Lgg_d2:
	v_mov_b32_e32 v21, s9
	s_add_i32 s9, s9, s11
	v_mov_b32_e32 v23, s9
	s_add_i32 s9, s9, s11
	v_mov_b32_e32 v24, s9
	s_add_i32 s9, s9, s11
	v_mov_b32_e32 v25, s9
	s_mov_b32 s58, 0
	global_atomic_add v20, v202, s[12:13]
.Lgg_spin:
	global_load_dword v22, v20, s[12:13] sc1
	global_load_dword v26, v21, s[12:13] sc1
	global_load_dword v27, v23, s[12:13] sc1
	global_load_dword v28, v24, s[12:13] sc1
	global_load_dword v29, v25, s[12:13] sc1
	s_waitcnt vmcnt(0)
	v_min_u32_e32 v26, v26, v27
	v_min3_u32 v26, v26, v28, v29
	v_cmp_gt_u32_e32 vcc, 4, v22
	s_cbranch_vccnz .Lgg_again
	v_cmp_gt_u32_e32 vcc, v30, v26
	s_cbranch_vccz .Lgg_done
.Lgg_again:
	s_sleep 1
	s_add_i32 s58, s58, 1
	s_cmp_lt_u32 s58, 0x40001
	s_cbranch_scc1 .Lgg_spin
